# L1-only invalidate also at out-proj->gate/up and at the FFN1-down->in-proj seam of attention layers (consumers after them read only own-XCD data)
# baseline (speedup 1.0000x reference)
.Linvd_b6n:
	s_waitcnt vmcnt(0)
.LBB0_1047:
	s_andn2_saveexec_b64 s[2:3], s[10:11]
	s_cbranch_execz .LBB0_1080
	s_mov_b64 s[10:11], exec
	buffer_wbl2 sc1
	s_waitcnt lgkmcnt(0)
	s_waitcnt vmcnt(0)
	v_mbcnt_lo_u32_b32 v0, s10, 0
	v_mbcnt_hi_u32_b32 v0, s11, v0
	v_cmp_eq_u32_e32 vcc, 0, v0
	s_and_saveexec_b64 s[12:13], vcc
	s_cbranch_execz .LBB0_1050
	s_bcnt1_i32_b64 s2, s[10:11]
	v_mov_b32_e32 v3, s2
	global_atomic_add v3, v254, v3, s[6:7] offset:1024 sc0

.LBB0_1342:
	s_or_b64 exec, exec, s[16:17]
	s_waitcnt lgkmcnt(0)
	v_readlane_b32 s2, v255, 40
	s_nop 0
	s_cmp_lg_u32 s2, 0
	s_cbranch_scc0 .Linvf_b2n
	s_cmp_lg_u64 s[10:11], 0
	s_cbranch_scc1 .Linv0_b2n
	v_readlane_b32 s2, v255, 23
	s_nop 0
	s_bitcmp0_b32 s2, 0
	s_cbranch_scc0 .Linvf_b2n
.Linv0_b2n:
	buffer_inv sc0
	s_branch .Linvd_b2n

.LBB0_1373:
	s_or_b64 exec, exec, s[12:13]
	s_mov_b64 s[6:7], exec
	v_mbcnt_lo_u32_b32 v0, s6, 0
	v_mbcnt_hi_u32_b32 v0, s7, v0
	v_cmp_eq_u32_e32 vcc, 0, v0
	s_waitcnt vmcnt(0)
	v_readlane_b32 s2, v255, 40
	s_nop 0
	s_cmp_lg_u32 s2, 0
	s_cbranch_scc0 .Linvf_b2j
	s_cmp_lg_u64 s[10:11], 0
	s_cbranch_scc1 .Linv0_b2j
	v_readlane_b32 s2, v255, 23
	s_nop 0
	s_bitcmp0_b32 s2, 0
	s_cbranch_scc0 .Linvf_b2j
